# phase_prep: waves 4-7 take token and S5 items in rotated order
# baseline (speedup 1.0000x reference)
.LBB0_267:
	s_mov_b32 s16, s46
	s_mov_b32 s2, s54
	s_add_i32 s16, s2, s16
	s_cmpk_gt_i32 s16, 0x7ff
	s_cbranch_scc1 .LBB0_560
.LBB0_268:
	s_mov_b32 s46, s16
	s_cmpk_gt_i32 s16, 0x1ff
	s_mov_b64 s[4:5], -1
	s_cbranch_scc0 .LBB0_349
	v_readfirstlane_b32 s47, v226
	s_lshr_b32 s47, s47, 8
	s_cmp_eq_u32 s47, 0
	s_cbranch_scc1 .Lprep_keep
	s_lshr_b32 s47, s16, 8
	s_cmp_le_u32 s47, 3
	s_movk_i32 s48, 0x400
	s_cselect_b32 s47, s48, 0xfffffe00
	s_add_i32 s16, s16, s47
.Lprep_keep:
	s_lshl_b32 s17, s16, 3
	s_cmpk_gt_u32 s16, 0x5ff
	s_cbranch_scc0 .LBB0_281
	s_load_dwordx2 s[4:5], s[0:1], 0x150
	v_add_u32_e32 v102, s17, v33
	v_and_b32_e32 v0, 0x7f, v102
	v_ashrrev_i32_e32 v16, 7, v102
	v_mul_u32_u24_e32 v0, 0x68000, v0
	v_lshlrev_b32_e32 v168, 2, v0
	v_lshlrev_b32_e32 v2, 4, v16
	s_waitcnt lgkmcnt(0)
	v_lshl_add_u64 v[0:1], s[4:5], 0, v[168:169]
	v_ashrrev_i32_e32 v3, 31, v2
	v_lshl_add_u64 v[0:1], v[2:3], 2, v[0:1]
	v_mov_b32_e32 v95, v169
	v_lshl_add_u64 v[8:9], v[0:1], 0, v[94:95]
	s_mov_b64 s[4:5], 0xd645f20
	v_lshl_add_u64 v[12:13], v[8:9], 0, s[4:5]
	v_add_co_u32_e32 v8, vcc, 0xd645000, v8
	global_load_dwordx4 v[0:3], v[12:13], off offset:32
	global_load_dwordx4 v[4:7], v[12:13], off offset:16
	v_addc_co_u32_e32 v9, vcc, 0, v9, vcc
	global_load_dwordx4 v[8:11], v[8:9], off offset:3872
	s_nop 0
	global_load_dwordx4 v[12:15], v[12:13], off offset:48
	v_readlane_b32 s2, v255, 26
	s_waitcnt vmcnt(0)
	ds_write_b128 v39, v[4:7] offset:16
	ds_write_b128 v39, v[0:3] offset:32
	s_waitcnt vmcnt(1)
	ds_write_b128 v39, v[8:11]
	s_waitcnt vmcnt(0)
	ds_write_b128 v39, v[12:15] offset:48
	s_waitcnt lgkmcnt(0)
	s_load_dwordx2 s[4:5], s[0:1], 0xa8
	v_add_u32_e32 v0, s2, v16
	v_ashrrev_i32_e32 v1, 31, v0
	s_brev_b32 s2, 18
	s_waitcnt lgkmcnt(0)
	v_lshl_add_u64 v[2:3], v[0:1], 2, s[4:5]
	global_load_dword v6, v[2:3], off
	s_load_dwordx2 s[4:5], s[0:1], 0x98
	v_lshl_or_b32 v2, v0, 6, v32
	v_ashrrev_i32_e32 v3, 31, v2
	v_lshlrev_b64 v[2:3], 2, v[2:3]
	s_waitcnt lgkmcnt(0)
	v_lshl_add_u64 v[4:5], s[4:5], 0, v[2:3]
	global_load_dword v108, v[4:5], off
	s_load_dwordx2 s[4:5], s[0:1], 0xa0
	s_waitcnt lgkmcnt(0)
	v_lshl_add_u64 v[2:3], s[4:5], 0, v[2:3]
	global_load_dword v109, v[2:3], off
	s_mov_b32 s4, 0x6dc9c883
	s_mov_b32 s5, 0x3fc45f30
	s_waitcnt vmcnt(2)
	v_mul_f32_e32 v2, 0x3fb8aa3b, v6
	v_exp_f32_e32 v2, v2
	s_waitcnt vmcnt(0)
	v_mul_f32_e32 v3, v2, v109
	v_cvt_f64_f32_e32 v[4:5], v3
	v_mul_f64 v[6:7], v[4:5], s[4:5]
	s_mov_b32 s4, 0x54442d18
	v_rndne_f64_e32 v[6:7], v[6:7]
	s_mov_b32 s5, 0xc01921fb
	v_fmac_f64_e32 v[4:5], s[4:5], v[6:7]
	v_cvt_f32_f64_e32 v3, v[4:5]
	v_and_b32_e32 v4, 0x7fffffff, v3
	v_lshrrev_b32_e32 v5, 23, v4
	v_and_b32_e32 v6, 0x7fffff, v4
	v_cmp_nlt_f32_e64 s[4:5], |v3|, s2
	v_add_u32_e32 v8, 0xffffff88, v5
	v_or_b32_e32 v5, 0x800000, v6
	s_and_saveexec_b64 s[8:9], s[4:5]
	s_xor_b64 s[18:19], exec, s[8:9]
	s_cbranch_execz .LBB0_272
	v_cmp_lt_u32_e32 vcc, 63, v8
	v_not_b32_e32 v6, 63
	s_mov_b32 s2, 0xfe5163ab
	v_cndmask_b32_e32 v6, 0, v6, vcc
	v_add_u32_e32 v6, v6, v8
	v_cmp_lt_u32_e64 s[8:9], 31, v6
	s_nop 1
	v_cndmask_b32_e64 v7, 0, v236, s[8:9]
	v_add_u32_e32 v6, v7, v6
	v_cmp_lt_u32_e64 s[10:11], 31, v6
	s_nop 1
	v_cndmask_b32_e64 v7, 0, v236, s[10:11]
	v_add_u32_e32 v9, v7, v6
	v_mad_u64_u32 v[6:7], s[14:15], v5, s2, 0
	v_mov_b32_e32 v168, v7
	s_mov_b32 s2, 0x3c439041
	v_mad_u64_u32 v[10:11], s[14:15], v5, s2, v[168:169]
	v_mov_b32_e32 v168, v11
	s_mov_b32 s2, 0xdb629599
	v_mad_u64_u32 v[12:13], s[14:15], v5, s2, v[168:169]
	v_mov_b32_e32 v168, v13
	s_mov_b32 s2, 0xf534ddc0
	v_mad_u64_u32 v[14:15], s[14:15], v5, s2, v[168:169]
	v_mov_b32_e32 v168, v15
	s_mov_b32 s2, 0xfc2757d1
	v_mad_u64_u32 v[16:17], s[14:15], v5, s2, v[168:169]
	v_mov_b32_e32 v168, v17
	s_mov_b32 s2, 0x4e441529
	v_mad_u64_u32 v[18:19], s[14:15], v5, s2, v[168:169]
	v_mov_b32_e32 v168, v19
	s_mov_b32 s2, 0xa2f9836e
	v_mad_u64_u32 v[20:21], s[14:15], v5, s2, v[168:169]
	v_cndmask_b32_e32 v7, v18, v14, vcc
	v_cndmask_b32_e32 v11, v20, v16, vcc
	v_cndmask_b32_e32 v15, v21, v18, vcc
	v_cndmask_b32_e64 v13, v11, v7, s[8:9]
	v_cndmask_b32_e64 v11, v15, v11, s[8:9]
	v_cndmask_b32_e32 v15, v16, v12, vcc
	v_cndmask_b32_e64 v7, v7, v15, s[8:9]
	v_cndmask_b32_e64 v11, v11, v13, s[10:11]
	v_cndmask_b32_e64 v13, v13, v7, s[10:11]
	v_sub_u32_e32 v16, 32, v9
	v_alignbit_b32 v17, v11, v13, v16
	v_cmp_eq_u32_e64 s[14:15], 0, v9
	v_cndmask_b32_e32 v10, v14, v10, vcc
	v_cndmask_b32_e32 v6, v12, v6, vcc
	v_cndmask_b32_e64 v9, v17, v11, s[14:15]
	v_cndmask_b32_e64 v11, v15, v10, s[8:9]
	v_cndmask_b32_e64 v7, v7, v11, s[10:11]
	v_alignbit_b32 v14, v13, v7, v16
	v_cndmask_b32_e64 v13, v14, v13, s[14:15]
	v_bfe_u32 v17, v9, 29, 1
	v_cndmask_b32_e64 v6, v10, v6, s[8:9]
	v_alignbit_b32 v14, v9, v13, 30
	v_sub_u32_e32 v18, 0, v17
	v_cndmask_b32_e64 v6, v11, v6, s[10:11]
	v_xor_b32_e32 v14, v14, v18
	v_alignbit_b32 v10, v7, v6, v16
	v_cndmask_b32_e64 v7, v10, v7, s[14:15]
	v_ffbh_u32_e32 v11, v14
	v_alignbit_b32 v10, v13, v7, 30
	v_min_u32_e32 v11, 32, v11
	v_alignbit_b32 v6, v7, v6, 30
	v_xor_b32_e32 v10, v10, v18
	v_sub_u32_e32 v12, 31, v11
	v_xor_b32_e32 v6, v6, v18
	v_alignbit_b32 v13, v14, v10, v12
	v_alignbit_b32 v6, v10, v6, v12
	v_alignbit_b32 v7, v13, v6, 9
	v_ffbh_u32_e32 v10, v7
	v_min_u32_e32 v10, 32, v10
	v_lshrrev_b32_e32 v15, 29, v9
	v_not_b32_e32 v12, v10
	v_alignbit_b32 v6, v7, v6, v12
	v_lshlrev_b32_e32 v7, 31, v15
	v_or_b32_e32 v12, 0x33000000, v7
	v_add_lshl_u32 v10, v10, v11, 23
	v_lshrrev_b32_e32 v6, 9, v6
	v_sub_u32_e32 v10, v12, v10
	v_or_b32_e32 v7, 0.5, v7
	v_lshlrev_b32_e32 v11, 23, v11
	v_or_b32_e32 v6, v10, v6
	v_lshrrev_b32_e32 v10, 9, v13
	v_sub_u32_e32 v7, v7, v11
	v_or_b32_e32 v7, v10, v7
	v_mul_f32_e32 v10, 0x3fc90fda, v7
	s_mov_b32 s2, 0x3fc90fda
	v_fma_f32 v11, v7, s2, -v10
	v_fmac_f32_e32 v11, 0x33a22168, v7
	v_fmac_f32_e32 v11, 0x3fc90fda, v6
	v_lshrrev_b32_e32 v7, 30, v9
	v_add_f32_e32 v6, v10, v11
	v_add_u32_e32 v7, v17, v7
